# strategy 2 (de-serialisation): prep0 cache_b_v and state_c transposes issue their four tile loads together with counted waits
# speedup vs baseline: 1.0083x; 1.0018x over previous
.LBB0_505:
	s_ashr_i32 s0, s8, 31
	s_lshr_b32 s0, s0, 29
	s_add_i32 s0, s8, s0
	s_ashr_i32 s0, s0, 3
	s_lshl_b32 s13, s0, 9
	s_sub_i32 s13, s12, s13
	s_ashr_i32 s1, s0, 31
	v_add_u32_e32 v12, s13, v141
	s_lshl_b64 s[22:23], s[0:1], 17
	v_ashrrev_i32_e32 v13, 31, v12
	v_lshl_add_u64 v[10:11], v[142:143], 0, s[22:23]
	v_lshlrev_b64 v[92:93], 8, v[12:13]
	v_lshl_add_u64 v[92:93], v[10:11], 0, v[92:93]
	global_load_dwordx4 v[76:79], v[92:93], off
	v_add_u32_e32 v94, 16, v12
	v_ashrrev_i32_e32 v95, 31, v94
	v_lshlrev_b64 v[94:95], 8, v[94:95]
	v_lshl_add_u64 v[94:95], v[10:11], 0, v[94:95]
	global_load_dwordx4 v[80:83], v[94:95], off
	v_add_u32_e32 v96, 32, v12
	v_ashrrev_i32_e32 v97, 31, v96
	v_lshlrev_b64 v[96:97], 8, v[96:97]
	v_lshl_add_u64 v[96:97], v[10:11], 0, v[96:97]
	global_load_dwordx4 v[84:87], v[96:97], off
	v_add_u32_e32 v98, 48, v12
	v_ashrrev_i32_e32 v99, 31, v98
	v_lshlrev_b64 v[98:99], 8, v[98:99]
	v_lshl_add_u64 v[98:99], v[10:11], 0, v[98:99]
	global_load_dwordx4 v[88:91], v[98:99], off
	v_add_u32_e32 v0, 0x400, v20
	s_lshl_b64 s[0:1], s[0:1], 16
	s_add_u32 s0, s9, s0
	s_addc_u32 s1, s11, s1
	s_add_i32 s8, s8, s44
	s_add_i32 s12, s12, s6
	s_cmpk_lt_i32 s8, 0x100
	s_waitcnt vmcnt(3)
	ds_write2_b32 v2, v76, v77 offset1:1
	ds_write2_b32 v2, v78, v79 offset0:2 offset1:3
	s_waitcnt vmcnt(2)
	ds_write2_b32 v3, v80, v81 offset1:1
	ds_write2_b32 v3, v82, v83 offset0:2 offset1:3
	s_waitcnt vmcnt(1)
	ds_write2_b32 v4, v84, v85 offset1:1
	ds_write2_b32 v4, v86, v87 offset0:2 offset1:3
	s_waitcnt vmcnt(0)
	ds_write2_b32 v5, v88, v89 offset1:1
	ds_write2_b32 v5, v90, v91 offset0:2 offset1:3
	s_waitcnt lgkmcnt(0)
	s_barrier
	ds_read2_b32 v[6:7], v20 offset1:65
	ds_read2_b32 v[8:9], v20 offset0:130 offset1:195
	ds_read2_b32 v[10:11], v0 offset0:4 offset1:69
	ds_read2_b32 v[12:13], v0 offset0:134 offset1:199
	v_add_u32_e32 v0, 0x800, v20
	ds_read2_b32 v[14:15], v0 offset0:8 offset1:73
	ds_read2_b32 v[16:17], v0 offset0:138 offset1:203
	v_add_u32_e32 v0, 0xc00, v20
	ds_read2_b32 v[22:23], v0 offset0:12 offset1:77
	ds_read2_b32 v[24:25], v0 offset0:142 offset1:207
	v_add_u32_e32 v0, s13, v138
	v_ashrrev_i32_e32 v26, 5, v0
	v_ashrrev_i32_e32 v27, 31, v26
	v_lshlrev_b64 v[26:27], 12, v[26:27]
	v_lshl_add_u64 v[26:27], s[0:1], 0, v[26:27]
	v_lshl_add_u64 v[26:27], v[26:27], 0, v[144:145]
	v_lshlrev_b32_e32 v0, 1, v140
	v_lshl_add_u64 v[26:27], v[26:27], 0, v[0:1]
	s_waitcnt lgkmcnt(6)
	v_and_b32_sdwa v0, v8, v193 dst_sel:DWORD dst_unused:UNUSED_PAD src0_sel:WORD_1 src1_sel:DWORD
	v_and_b32_sdwa v19, v6, v193 dst_sel:DWORD dst_unused:UNUSED_PAD src0_sel:WORD_1 src1_sel:DWORD
	v_add3_u32 v0, v8, v0, s87
	v_and_b32_sdwa v8, v9, v193 dst_sel:DWORD dst_unused:UNUSED_PAD src0_sel:WORD_1 src1_sel:DWORD
	v_add3_u32 v6, v6, v19, s87
	v_and_b32_sdwa v19, v7, v193 dst_sel:DWORD dst_unused:UNUSED_PAD src0_sel:WORD_1 src1_sel:DWORD
	v_add3_u32 v8, v9, v8, s87
	v_add3_u32 v7, v7, v19, s87
	v_and_b32_e32 v8, 0xffff0000, v8
	v_and_b32_e32 v9, 0xffff0000, v7
	v_or_b32_sdwa v7, v8, v0 dst_sel:DWORD dst_unused:UNUSED_PAD src0_sel:DWORD src1_sel:WORD_1
	s_waitcnt lgkmcnt(5)
	v_and_b32_sdwa v8, v10, v193 dst_sel:DWORD dst_unused:UNUSED_PAD src0_sel:WORD_1 src1_sel:DWORD
	v_or_b32_sdwa v6, v9, v6 dst_sel:DWORD dst_unused:UNUSED_PAD src0_sel:DWORD src1_sel:WORD_1
	v_add3_u32 v8, v10, v8, s87
	s_waitcnt lgkmcnt(4)
	v_and_b32_sdwa v9, v13, v193 dst_sel:DWORD dst_unused:UNUSED_PAD src0_sel:WORD_1 src1_sel:DWORD
	v_and_b32_sdwa v10, v11, v193 dst_sel:DWORD dst_unused:UNUSED_PAD src0_sel:WORD_1 src1_sel:DWORD
	v_and_b32_sdwa v0, v12, v193 dst_sel:DWORD dst_unused:UNUSED_PAD src0_sel:WORD_1 src1_sel:DWORD
	v_add3_u32 v9, v13, v9, s87
	v_add3_u32 v10, v11, v10, s87
	v_add3_u32 v0, v12, v0, s87
	v_and_b32_e32 v9, 0xffff0000, v9
	v_and_b32_e32 v10, 0xffff0000, v10
	v_or_b32_sdwa v9, v9, v0 dst_sel:DWORD dst_unused:UNUSED_PAD src0_sel:DWORD src1_sel:WORD_1
	v_or_b32_sdwa v8, v10, v8 dst_sel:DWORD dst_unused:UNUSED_PAD src0_sel:DWORD src1_sel:WORD_1
	global_store_dwordx4 v[26:27], v[6:9], off
	s_waitcnt lgkmcnt(2)
	v_and_b32_sdwa v0, v16, v193 dst_sel:DWORD dst_unused:UNUSED_PAD src0_sel:WORD_1 src1_sel:DWORD
	v_add3_u32 v0, v16, v0, s87
	v_and_b32_sdwa v7, v17, v193 dst_sel:DWORD dst_unused:UNUSED_PAD src0_sel:WORD_1 src1_sel:DWORD
	v_and_b32_sdwa v8, v15, v193 dst_sel:DWORD dst_unused:UNUSED_PAD src0_sel:WORD_1 src1_sel:DWORD
	v_and_b32_sdwa v6, v14, v193 dst_sel:DWORD dst_unused:UNUSED_PAD src0_sel:WORD_1 src1_sel:DWORD
	v_add3_u32 v7, v17, v7, s87
	v_add3_u32 v8, v15, v8, s87
	v_add3_u32 v6, v14, v6, s87
	v_and_b32_e32 v7, 0xffff0000, v7
	v_and_b32_e32 v8, 0xffff0000, v8
	s_waitcnt lgkmcnt(0)
	v_and_b32_sdwa v9, v25, v193 dst_sel:DWORD dst_unused:UNUSED_PAD src0_sel:WORD_1 src1_sel:DWORD
	v_and_b32_sdwa v10, v23, v193 dst_sel:DWORD dst_unused:UNUSED_PAD src0_sel:WORD_1 src1_sel:DWORD
	v_or_b32_sdwa v7, v7, v0 dst_sel:DWORD dst_unused:UNUSED_PAD src0_sel:DWORD src1_sel:WORD_1
	v_or_b32_sdwa v6, v8, v6 dst_sel:DWORD dst_unused:UNUSED_PAD src0_sel:DWORD src1_sel:WORD_1
	v_and_b32_sdwa v0, v24, v193 dst_sel:DWORD dst_unused:UNUSED_PAD src0_sel:WORD_1 src1_sel:DWORD
	v_and_b32_sdwa v8, v22, v193 dst_sel:DWORD dst_unused:UNUSED_PAD src0_sel:WORD_1 src1_sel:DWORD
	v_add3_u32 v9, v25, v9, s87
	v_add3_u32 v10, v23, v10, s87
	v_add3_u32 v8, v22, v8, s87
	v_add3_u32 v0, v24, v0, s87
	v_and_b32_e32 v9, 0xffff0000, v9
	v_and_b32_e32 v10, 0xffff0000, v10
	v_or_b32_sdwa v9, v9, v0 dst_sel:DWORD dst_unused:UNUSED_PAD src0_sel:DWORD src1_sel:WORD_1
	v_or_b32_sdwa v8, v10, v8 dst_sel:DWORD dst_unused:UNUSED_PAD src0_sel:DWORD src1_sel:WORD_1
	global_store_dwordx4 v[26:27], v[6:9], off offset:16
	s_barrier
	s_cbranch_scc1 .LBB0_505

.LBB0_508:
	global_load_dwordx4 v[76:79], v[2:3], off
	v_add_co_u32_e32 v94, vcc, 0x1000, v2
	s_nop 1
	v_addc_co_u32_e32 v95, vcc, 0, v3, vcc
	global_load_dwordx4 v[80:83], v[94:95], off
	v_add_co_u32_e32 v96, vcc, 0x2000, v2
	s_nop 1
	v_addc_co_u32_e32 v97, vcc, 0, v3, vcc
	global_load_dwordx4 v[84:87], v[96:97], off
	v_add_co_u32_e32 v98, vcc, 0x3000, v2
	s_nop 1
	v_addc_co_u32_e32 v99, vcc, 0, v3, vcc
	global_load_dwordx4 v[88:91], v[98:99], off
	v_add_u32_e32 v9, 0x400, v20
	s_add_i32 s0, s0, s44
	s_cmp_lt_i32 s0, 64
	s_nop 1
	v_lshl_add_u64 v[2:3], v[2:3], 0, s[22:23]
	s_waitcnt vmcnt(3)
	ds_write2_b32 v0, v76, v77 offset1:1
	ds_write2_b32 v0, v78, v79 offset0:2 offset1:3
	s_waitcnt vmcnt(2)
	ds_write2_b32 v6, v80, v81 offset1:1
	ds_write2_b32 v6, v82, v83 offset0:2 offset1:3
	s_waitcnt vmcnt(1)
	ds_write2_b32 v7, v84, v85 offset1:1
	ds_write2_b32 v7, v86, v87 offset0:2 offset1:3
	s_waitcnt vmcnt(0)
	ds_write2_b32 v8, v88, v89 offset1:1
	ds_write2_b32 v8, v90, v91 offset0:2 offset1:3
	s_waitcnt lgkmcnt(0)
	s_barrier
	ds_read2_b32 v[10:11], v20 offset1:65
	ds_read2_b32 v[12:13], v20 offset0:130 offset1:195
	ds_read2_b32 v[14:15], v9 offset0:4 offset1:69
	ds_read2_b32 v[16:17], v9 offset0:134 offset1:199
	v_add_u32_e32 v9, 0x800, v20
	ds_read2_b32 v[18:19], v9 offset0:8 offset1:73
	ds_read2_b32 v[22:23], v9 offset0:138 offset1:203
	v_add_u32_e32 v9, 0xc00, v20
	ds_read2_b32 v[24:25], v9 offset0:12 offset1:77
	ds_read2_b32 v[26:27], v9 offset0:142 offset1:207
	s_waitcnt lgkmcnt(6)
	v_and_b32_sdwa v9, v12, v193 dst_sel:DWORD dst_unused:UNUSED_PAD src0_sel:WORD_1 src1_sel:DWORD
	v_and_b32_sdwa v21, v10, v193 dst_sel:DWORD dst_unused:UNUSED_PAD src0_sel:WORD_1 src1_sel:DWORD
	v_add3_u32 v9, v12, v9, s87
	v_and_b32_sdwa v12, v13, v193 dst_sel:DWORD dst_unused:UNUSED_PAD src0_sel:WORD_1 src1_sel:DWORD
	v_add3_u32 v10, v10, v21, s87
	v_and_b32_sdwa v21, v11, v193 dst_sel:DWORD dst_unused:UNUSED_PAD src0_sel:WORD_1 src1_sel:DWORD
	v_add3_u32 v12, v13, v12, s87
	v_add3_u32 v11, v11, v21, s87
	v_and_b32_e32 v12, 0xffff0000, v12
	v_and_b32_e32 v13, 0xffff0000, v11
	v_or_b32_sdwa v11, v12, v9 dst_sel:DWORD dst_unused:UNUSED_PAD src0_sel:DWORD src1_sel:WORD_1
	s_waitcnt lgkmcnt(5)
	v_and_b32_sdwa v12, v14, v193 dst_sel:DWORD dst_unused:UNUSED_PAD src0_sel:WORD_1 src1_sel:DWORD
	v_or_b32_sdwa v10, v13, v10 dst_sel:DWORD dst_unused:UNUSED_PAD src0_sel:DWORD src1_sel:WORD_1
	v_add3_u32 v12, v14, v12, s87
	s_waitcnt lgkmcnt(4)
	v_and_b32_sdwa v13, v17, v193 dst_sel:DWORD dst_unused:UNUSED_PAD src0_sel:WORD_1 src1_sel:DWORD
	v_and_b32_sdwa v14, v15, v193 dst_sel:DWORD dst_unused:UNUSED_PAD src0_sel:WORD_1 src1_sel:DWORD
	v_and_b32_sdwa v9, v16, v193 dst_sel:DWORD dst_unused:UNUSED_PAD src0_sel:WORD_1 src1_sel:DWORD
	v_add3_u32 v13, v17, v13, s87
	v_add3_u32 v14, v15, v14, s87
	v_add3_u32 v9, v16, v9, s87
	v_and_b32_e32 v13, 0xffff0000, v13
	v_and_b32_e32 v14, 0xffff0000, v14
	v_or_b32_sdwa v13, v13, v9 dst_sel:DWORD dst_unused:UNUSED_PAD src0_sel:DWORD src1_sel:WORD_1
	v_or_b32_sdwa v12, v14, v12 dst_sel:DWORD dst_unused:UNUSED_PAD src0_sel:DWORD src1_sel:WORD_1
	global_store_dwordx4 v[4:5], v[10:13], off offset:-16
	s_waitcnt lgkmcnt(2)
	v_and_b32_sdwa v9, v22, v193 dst_sel:DWORD dst_unused:UNUSED_PAD src0_sel:WORD_1 src1_sel:DWORD
	v_add3_u32 v9, v22, v9, s87
	v_and_b32_sdwa v11, v23, v193 dst_sel:DWORD dst_unused:UNUSED_PAD src0_sel:WORD_1 src1_sel:DWORD
	v_and_b32_sdwa v12, v19, v193 dst_sel:DWORD dst_unused:UNUSED_PAD src0_sel:WORD_1 src1_sel:DWORD
	v_and_b32_sdwa v10, v18, v193 dst_sel:DWORD dst_unused:UNUSED_PAD src0_sel:WORD_1 src1_sel:DWORD
	v_add3_u32 v11, v23, v11, s87
	v_add3_u32 v12, v19, v12, s87
	v_add3_u32 v10, v18, v10, s87
	v_and_b32_e32 v11, 0xffff0000, v11
	v_and_b32_e32 v12, 0xffff0000, v12
	s_waitcnt lgkmcnt(0)
	v_and_b32_sdwa v13, v27, v193 dst_sel:DWORD dst_unused:UNUSED_PAD src0_sel:WORD_1 src1_sel:DWORD
	v_and_b32_sdwa v14, v25, v193 dst_sel:DWORD dst_unused:UNUSED_PAD src0_sel:WORD_1 src1_sel:DWORD
	v_or_b32_sdwa v11, v11, v9 dst_sel:DWORD dst_unused:UNUSED_PAD src0_sel:DWORD src1_sel:WORD_1
	v_or_b32_sdwa v10, v12, v10 dst_sel:DWORD dst_unused:UNUSED_PAD src0_sel:DWORD src1_sel:WORD_1
	v_and_b32_sdwa v9, v26, v193 dst_sel:DWORD dst_unused:UNUSED_PAD src0_sel:WORD_1 src1_sel:DWORD
	v_and_b32_sdwa v12, v24, v193 dst_sel:DWORD dst_unused:UNUSED_PAD src0_sel:WORD_1 src1_sel:DWORD
	v_add3_u32 v13, v27, v13, s87
	v_add3_u32 v14, v25, v14, s87
	v_add3_u32 v12, v24, v12, s87
	v_add3_u32 v9, v26, v9, s87
	v_and_b32_e32 v13, 0xffff0000, v13
	v_and_b32_e32 v14, 0xffff0000, v14
	v_or_b32_sdwa v13, v13, v9 dst_sel:DWORD dst_unused:UNUSED_PAD src0_sel:DWORD src1_sel:WORD_1
	v_or_b32_sdwa v12, v14, v12 dst_sel:DWORD dst_unused:UNUSED_PAD src0_sel:DWORD src1_sel:WORD_1
	global_store_dwordx4 v[4:5], v[10:13], off
	v_lshl_add_u64 v[4:5], v[4:5], 0, s[26:27]
	s_barrier
	s_cbranch_scc1 .LBB0_508
